# sample attention rewrite (streamed K/V ring, 4 tokens of a (batch,head) per WG, 256B-contiguous lane mapping) + P2 two-group stage order + P3 scan prefetch
# speedup vs baseline: 1.0225x; 1.0049x over previous
; __device__ __forceinline__ float fexp2(float x) { return __builtin_amdgcn_exp2f(x); }
; __device__ __forceinline__ void attn_sample_item(const P& p, int wi, int lane) {
;     ...
;         for (int jj = 0; jj < 33; ++jj) {
;             const int j = 4 * jj + kg; const bool valid = j <= 128; const int jc = valid ? j : 128;
;             const int idx = 2048 + i - d * jc;
;             f32x4 k0, k1, v0, v1;
;             if (idx < 2048) { const size_t off = (((size_t)bs * 2048 + idx) * 8 + h) * 128 + 8 * li;
;                 k0 = __builtin_nontemporal_load((const f32x4*)(p.cache_k + off)); k1 = __builtin_nontemporal_load((const f32x4*)(p.cache_k + off + 4)); v0 = __builtin_nontemporal_load((const f32x4*)(p.cache_v + off)); v1 = __builtin_nontemporal_load((const f32x4*)(p.cache_v + off + 4)); }
;             else { const int nr = bs * 4 + (idx - 2048); const float rsn = rstd1[TP + nr]; const int c0 = 4096 + h * 128 + 8 * li;
;                 k0 = acc1_4(ACC1, nr, c0) * rsn; k1 = acc1_4(ACC1, nr, c0 + 4) * rsn; v0 = acc1_4(ACC1, nr, c0 + 1024) * rsn; v1 = acc1_4(ACC1, nr, c0 + 1028) * rsn; }
;             float dot = (q[0] * k0[0] + q[1] * k0[1]) + (q[2] * k0[2] + q[3] * k0[3]) + (q[4] * k1[0] + q[5] * k1[1]) + (q[6] * k1[2] + q[7] * k1[3]);
;             dot += __shfl_xor(dot, 1); dot += __shfl_xor(dot, 2); dot += __shfl_xor(dot, 4); dot += __shfl_xor(dot, 8);
;             const float s = valid ? dot - sl * (float)(d * j) : -INFINITY;
;             const float mn = fmaxf(m, s), sc = fexp2(m - mn), pe = fexp2(s - mn);
;             l = l * sc + pe;
;             acc[0] = acc[0] * sc + pe * v0[0]; acc[1] = acc[1] * sc + pe * v0[1]; acc[2] = acc[2] * sc + pe * v0[2]; acc[3] = acc[3] * sc + pe * v0[3];
;             acc[4] = acc[4] * sc + pe * v1[0]; acc[5] = acc[5] * sc + pe * v1[1]; acc[6] = acc[6] * sc + pe * v1[2]; acc[7] = acc[7] * sc + pe * v1[3];
;             m = mn;
;         }
.Las_sw4:
	s_waitcnt vmcnt(28)
	v_fma_f32 v197, v160, v0, v194
	v_fmac_f32_e32 v197, v161, v1
	v_fmac_f32_e32 v197, v162, v2
	v_fmac_f32_e32 v197, v163, v3
	v_fmac_f32_e32 v197, v164, v4
	v_fmac_f32_e32 v197, v165, v5
	v_fmac_f32_e32 v197, v166, v6
	v_fmac_f32_e32 v197, v167, v7
	s_nop 1
	v_add_f32_dpp v197, v197, v197 row_ror:8 row_mask:0xf bank_mask:0xf
	s_nop 1
	v_add_f32_dpp v197, v197, v197 row_ror:4 row_mask:0xf bank_mask:0xf
	s_nop 1
	v_add_f32_dpp v197, v197, v197 row_ror:2 row_mask:0xf bank_mask:0xf
	s_nop 1
	v_add_f32_dpp v197, v197, v197 row_ror:1 row_mask:0xf bank_mask:0xf
	v_max_f32_e32 v198, v192, v197
	v_sub_f32_e32 v199, v192, v198
	v_sub_f32_e32 v200, v197, v198
	v_exp_f32_e32 v199, v199
	v_exp_f32_e32 v200, v200
	v_mov_b32_e32 v192, v198
	v_fma_f32 v193, v193, v199, v200
	v_mul_f32_e32 v168, v168, v199
	v_mul_f32_e32 v169, v169, v199
	v_mul_f32_e32 v170, v170, v199
	v_mul_f32_e32 v171, v171, v199
	v_mul_f32_e32 v172, v172, v199
	v_mul_f32_e32 v173, v173, v199
	v_mul_f32_e32 v174, v174, v199
	v_mul_f32_e32 v175, v175, v199
	v_fmac_f32_e32 v168, v200, v8
	v_fmac_f32_e32 v169, v200, v9
	v_fmac_f32_e32 v170, v200, v10
	v_fmac_f32_e32 v171, v200, v11
	v_fmac_f32_e32 v172, v200, v12
	v_fmac_f32_e32 v173, v200, v13
	v_fmac_f32_e32 v174, v200, v14
	v_fmac_f32_e32 v175, v200, v15
	v_add_f32_e32 v194, v194, v196
	v_add_u32_e32 v195, s42, v195
	global_load_dwordx4 v[0:3], v195, s[20:21] nt
	global_load_dwordx4 v[4:7], v195, s[20:21] offset:256 nt
	global_load_dwordx4 v[8:11], v195, s[24:25] nt
	global_load_dwordx4 v[12:15], v195, s[24:25] offset:256 nt
.Las_slot1:
	s_waitcnt vmcnt(28)
	v_fma_f32 v197, v160, v16, v194
	v_fmac_f32_e32 v197, v161, v17
	v_fmac_f32_e32 v197, v162, v18
	v_fmac_f32_e32 v197, v163, v19
	v_fmac_f32_e32 v197, v164, v20
	v_fmac_f32_e32 v197, v165, v21
	v_fmac_f32_e32 v197, v166, v22
	v_fmac_f32_e32 v197, v167, v23
	s_nop 1
	v_add_f32_dpp v197, v197, v197 row_ror:8 row_mask:0xf bank_mask:0xf
	s_nop 1
	v_add_f32_dpp v197, v197, v197 row_ror:4 row_mask:0xf bank_mask:0xf
	s_nop 1
	v_add_f32_dpp v197, v197, v197 row_ror:2 row_mask:0xf bank_mask:0xf
	s_nop 1
	v_add_f32_dpp v197, v197, v197 row_ror:1 row_mask:0xf bank_mask:0xf
	v_max_f32_e32 v198, v192, v197
	v_sub_f32_e32 v199, v192, v198
	v_sub_f32_e32 v200, v197, v198
	v_exp_f32_e32 v199, v199
	v_exp_f32_e32 v200, v200
	v_mov_b32_e32 v192, v198
	v_fma_f32 v193, v193, v199, v200
	v_mul_f32_e32 v168, v168, v199
	v_mul_f32_e32 v169, v169, v199
	v_mul_f32_e32 v170, v170, v199
	v_mul_f32_e32 v171, v171, v199
	v_mul_f32_e32 v172, v172, v199
	v_mul_f32_e32 v173, v173, v199
	v_mul_f32_e32 v174, v174, v199
	v_mul_f32_e32 v175, v175, v199
	v_fmac_f32_e32 v168, v200, v24
	v_fmac_f32_e32 v169, v200, v25
	v_fmac_f32_e32 v170, v200, v26
	v_fmac_f32_e32 v171, v200, v27
	v_fmac_f32_e32 v172, v200, v28
	v_fmac_f32_e32 v173, v200, v29
	v_fmac_f32_e32 v174, v200, v30
	v_fmac_f32_e32 v175, v200, v31
	v_add_f32_e32 v194, v194, v196
	v_add_u32_e32 v195, s42, v195
	global_load_dwordx4 v[16:19], v195, s[20:21] nt
	global_load_dwordx4 v[20:23], v195, s[20:21] offset:256 nt
	global_load_dwordx4 v[24:27], v195, s[24:25] nt
	global_load_dwordx4 v[28:31], v195, s[24:25] offset:256 nt
	s_waitcnt vmcnt(28)
	v_fma_f32 v197, v160, v32, v194
	v_fmac_f32_e32 v197, v161, v33
	v_fmac_f32_e32 v197, v162, v34
	v_fmac_f32_e32 v197, v163, v35
	v_fmac_f32_e32 v197, v164, v36
	v_fmac_f32_e32 v197, v165, v37
	v_fmac_f32_e32 v197, v166, v38
	v_fmac_f32_e32 v197, v167, v39
	s_nop 1
	v_add_f32_dpp v197, v197, v197 row_ror:8 row_mask:0xf bank_mask:0xf
	s_nop 1
	v_add_f32_dpp v197, v197, v197 row_ror:4 row_mask:0xf bank_mask:0xf
	s_nop 1
	v_add_f32_dpp v197, v197, v197 row_ror:2 row_mask:0xf bank_mask:0xf
	s_nop 1
	v_add_f32_dpp v197, v197, v197 row_ror:1 row_mask:0xf bank_mask:0xf
	v_max_f32_e32 v198, v192, v197
	v_sub_f32_e32 v199, v192, v198
	v_sub_f32_e32 v200, v197, v198
	v_exp_f32_e32 v199, v199
	v_exp_f32_e32 v200, v200
	v_mov_b32_e32 v192, v198
	v_fma_f32 v193, v193, v199, v200
	v_mul_f32_e32 v168, v168, v199
	v_mul_f32_e32 v169, v169, v199
	v_mul_f32_e32 v170, v170, v199
	v_mul_f32_e32 v171, v171, v199
	v_mul_f32_e32 v172, v172, v199
	v_mul_f32_e32 v173, v173, v199
	v_mul_f32_e32 v174, v174, v199
	v_mul_f32_e32 v175, v175, v199
	v_fmac_f32_e32 v168, v200, v40
	v_fmac_f32_e32 v169, v200, v41
	v_fmac_f32_e32 v170, v200, v42
	v_fmac_f32_e32 v171, v200, v43
	v_fmac_f32_e32 v172, v200, v44
	v_fmac_f32_e32 v173, v200, v45
	v_fmac_f32_e32 v174, v200, v46
	v_fmac_f32_e32 v175, v200, v47
	v_add_f32_e32 v194, v194, v196
	v_add_u32_e32 v195, s42, v195
	global_load_dwordx4 v[32:35], v195, s[20:21] nt
	global_load_dwordx4 v[36:39], v195, s[20:21] offset:256 nt
	global_load_dwordx4 v[40:43], v195, s[24:25] nt
	global_load_dwordx4 v[44:47], v195, s[24:25] offset:256 nt
	s_waitcnt vmcnt(28)
	v_fma_f32 v197, v160, v48, v194
	v_fmac_f32_e32 v197, v161, v49
	v_fmac_f32_e32 v197, v162, v50
	v_fmac_f32_e32 v197, v163, v51
	v_fmac_f32_e32 v197, v164, v52
	v_fmac_f32_e32 v197, v165, v53
	v_fmac_f32_e32 v197, v166, v54
	v_fmac_f32_e32 v197, v167, v55
	s_nop 1
	v_add_f32_dpp v197, v197, v197 row_ror:8 row_mask:0xf bank_mask:0xf
	s_nop 1
	v_add_f32_dpp v197, v197, v197 row_ror:4 row_mask:0xf bank_mask:0xf
	s_nop 1
	v_add_f32_dpp v197, v197, v197 row_ror:2 row_mask:0xf bank_mask:0xf
	s_nop 1
	v_add_f32_dpp v197, v197, v197 row_ror:1 row_mask:0xf bank_mask:0xf
	v_max_f32_e32 v198, v192, v197
	v_sub_f32_e32 v199, v192, v198
	v_sub_f32_e32 v200, v197, v198
	v_exp_f32_e32 v199, v199
	v_exp_f32_e32 v200, v200
	v_mov_b32_e32 v192, v198
	v_fma_f32 v193, v193, v199, v200
	v_mul_f32_e32 v168, v168, v199
	v_mul_f32_e32 v169, v169, v199
	v_mul_f32_e32 v170, v170, v199
	v_mul_f32_e32 v171, v171, v199
	v_mul_f32_e32 v172, v172, v199
	v_mul_f32_e32 v173, v173, v199
	v_mul_f32_e32 v174, v174, v199
	v_mul_f32_e32 v175, v175, v199
	v_fmac_f32_e32 v168, v200, v56
	v_fmac_f32_e32 v169, v200, v57
	v_fmac_f32_e32 v170, v200, v58
	v_fmac_f32_e32 v171, v200, v59
	v_fmac_f32_e32 v172, v200, v60
	v_fmac_f32_e32 v173, v200, v61
	v_fmac_f32_e32 v174, v200, v62
	v_fmac_f32_e32 v175, v200, v63
	v_add_f32_e32 v194, v194, v196
	v_add_u32_e32 v195, s42, v195
	global_load_dwordx4 v[48:51], v195, s[20:21] nt
	global_load_dwordx4 v[52:55], v195, s[20:21] offset:256 nt
	global_load_dwordx4 v[56:59], v195, s[24:25] nt
	global_load_dwordx4 v[60:63], v195, s[24:25] offset:256 nt
	s_waitcnt vmcnt(28)
; __device__ __forceinline__ float fexp2(float x) { return __builtin_amdgcn_exp2f(x); }
; __device__ __forceinline__ void attn_sample_item(const P& p, int wi, int lane) {
;     ...
;         for (int jj = 0; jj < 33; ++jj) {
;             const int j = 4 * jj + kg; const bool valid = j <= 128; const int jc = valid ? j : 128;
;             const int idx = 2048 + i - d * jc;
;             f32x4 k0, k1, v0, v1;
;             if (idx < 2048) { const size_t off = (((size_t)bs * 2048 + idx) * 8 + h) * 128 + 8 * li;
;                 k0 = __builtin_nontemporal_load((const f32x4*)(p.cache_k + off)); k1 = __builtin_nontemporal_load((const f32x4*)(p.cache_k + off + 4)); v0 = __builtin_nontemporal_load((const f32x4*)(p.cache_v + off)); v1 = __builtin_nontemporal_load((const f32x4*)(p.cache_v + off + 4)); }
;             else { const int nr = bs * 4 + (idx - 2048); const float rsn = rstd1[TP + nr]; const int c0 = 4096 + h * 128 + 8 * li;
;                 k0 = acc1_4(ACC1, nr, c0) * rsn; k1 = acc1_4(ACC1, nr, c0 + 4) * rsn; v0 = acc1_4(ACC1, nr, c0 + 1024) * rsn; v1 = acc1_4(ACC1, nr, c0 + 1028) * rsn; }
;             float dot = (q[0] * k0[0] + q[1] * k0[1]) + (q[2] * k0[2] + q[3] * k0[3]) + (q[4] * k1[0] + q[5] * k1[1]) + (q[6] * k1[2] + q[7] * k1[3]);
;             dot += __shfl_xor(dot, 1); dot += __shfl_xor(dot, 2); dot += __shfl_xor(dot, 4); dot += __shfl_xor(dot, 8);
;             const float s = valid ? dot - sl * (float)(d * j) : -INFINITY;
;             const float mn = fmaxf(m, s), sc = fexp2(m - mn), pe = fexp2(s - mn);
;             l = l * sc + pe;
;             acc[0] = acc[0] * sc + pe * v0[0]; acc[1] = acc[1] * sc + pe * v0[1]; acc[2] = acc[2] * sc + pe * v0[2]; acc[3] = acc[3] * sc + pe * v0[3];
;             acc[4] = acc[4] * sc + pe * v1[0]; acc[5] = acc[5] * sc + pe * v1[1]; acc[6] = acc[6] * sc + pe * v1[2]; acc[7] = acc[7] * sc + pe * v1[3];
;             m = mn;
;         }
	v_fma_f32 v197, v160, v64, v194
	v_fmac_f32_e32 v197, v161, v65
	v_fmac_f32_e32 v197, v162, v66
	v_fmac_f32_e32 v197, v163, v67
	v_fmac_f32_e32 v197, v164, v68
	v_fmac_f32_e32 v197, v165, v69
	v_fmac_f32_e32 v197, v166, v70
	v_fmac_f32_e32 v197, v167, v71
	s_nop 1
	v_add_f32_dpp v197, v197, v197 row_ror:8 row_mask:0xf bank_mask:0xf
	s_nop 1
	v_add_f32_dpp v197, v197, v197 row_ror:4 row_mask:0xf bank_mask:0xf
	s_nop 1
	v_add_f32_dpp v197, v197, v197 row_ror:2 row_mask:0xf bank_mask:0xf
	s_nop 1
	v_add_f32_dpp v197, v197, v197 row_ror:1 row_mask:0xf bank_mask:0xf
	v_max_f32_e32 v198, v192, v197
	v_sub_f32_e32 v199, v192, v198
	v_sub_f32_e32 v200, v197, v198
	v_exp_f32_e32 v199, v199
	v_exp_f32_e32 v200, v200
	v_mov_b32_e32 v192, v198
	v_fma_f32 v193, v193, v199, v200
	v_mul_f32_e32 v168, v168, v199
	v_mul_f32_e32 v169, v169, v199
	v_mul_f32_e32 v170, v170, v199
	v_mul_f32_e32 v171, v171, v199
	v_mul_f32_e32 v172, v172, v199
	v_mul_f32_e32 v173, v173, v199
	v_mul_f32_e32 v174, v174, v199
	v_mul_f32_e32 v175, v175, v199
	v_fmac_f32_e32 v168, v200, v72
	v_fmac_f32_e32 v169, v200, v73
	v_fmac_f32_e32 v170, v200, v74
	v_fmac_f32_e32 v171, v200, v75
	v_fmac_f32_e32 v172, v200, v76
	v_fmac_f32_e32 v173, v200, v77
	v_fmac_f32_e32 v174, v200, v78
	v_fmac_f32_e32 v175, v200, v79
	v_add_f32_e32 v194, v194, v196
	v_add_u32_e32 v195, s42, v195
	global_load_dwordx4 v[64:67], v195, s[20:21] nt
	global_load_dwordx4 v[68:71], v195, s[20:21] offset:256 nt
	global_load_dwordx4 v[72:75], v195, s[24:25] nt
	global_load_dwordx4 v[76:79], v195, s[24:25] offset:256 nt
	s_waitcnt vmcnt(28)
	v_fma_f32 v197, v160, v80, v194
	v_fmac_f32_e32 v197, v161, v81
	v_fmac_f32_e32 v197, v162, v82
	v_fmac_f32_e32 v197, v163, v83
	v_fmac_f32_e32 v197, v164, v84
	v_fmac_f32_e32 v197, v165, v85
	v_fmac_f32_e32 v197, v166, v86
	v_fmac_f32_e32 v197, v167, v87
	s_nop 1
	v_add_f32_dpp v197, v197, v197 row_ror:8 row_mask:0xf bank_mask:0xf
	s_nop 1
	v_add_f32_dpp v197, v197, v197 row_ror:4 row_mask:0xf bank_mask:0xf
	s_nop 1
	v_add_f32_dpp v197, v197, v197 row_ror:2 row_mask:0xf bank_mask:0xf
	s_nop 1
	v_add_f32_dpp v197, v197, v197 row_ror:1 row_mask:0xf bank_mask:0xf
	v_max_f32_e32 v198, v192, v197
	v_sub_f32_e32 v199, v192, v198
	v_sub_f32_e32 v200, v197, v198
	v_exp_f32_e32 v199, v199
	v_exp_f32_e32 v200, v200
	v_mov_b32_e32 v192, v198
	v_fma_f32 v193, v193, v199, v200
	v_mul_f32_e32 v168, v168, v199
	v_mul_f32_e32 v169, v169, v199
	v_mul_f32_e32 v170, v170, v199
	v_mul_f32_e32 v171, v171, v199
	v_mul_f32_e32 v172, v172, v199
	v_mul_f32_e32 v173, v173, v199
	v_mul_f32_e32 v174, v174, v199
	v_mul_f32_e32 v175, v175, v199
	v_fmac_f32_e32 v168, v200, v88
	v_fmac_f32_e32 v169, v200, v89
	v_fmac_f32_e32 v170, v200, v90
	v_fmac_f32_e32 v171, v200, v91
	v_fmac_f32_e32 v172, v200, v92
	v_fmac_f32_e32 v173, v200, v93
	v_fmac_f32_e32 v174, v200, v94
	v_fmac_f32_e32 v175, v200, v95
	v_add_f32_e32 v194, v194, v196
	v_add_u32_e32 v195, s42, v195
	global_load_dwordx4 v[80:83], v195, s[20:21] nt
	global_load_dwordx4 v[84:87], v195, s[20:21] offset:256 nt
	global_load_dwordx4 v[88:91], v195, s[24:25] nt
	global_load_dwordx4 v[92:95], v195, s[24:25] offset:256 nt
	s_waitcnt vmcnt(28)
	v_fma_f32 v197, v160, v96, v194
	v_fmac_f32_e32 v197, v161, v97
	v_fmac_f32_e32 v197, v162, v98
	v_fmac_f32_e32 v197, v163, v99
	v_fmac_f32_e32 v197, v164, v100
	v_fmac_f32_e32 v197, v165, v101
	v_fmac_f32_e32 v197, v166, v102
	v_fmac_f32_e32 v197, v167, v103
	s_nop 1
	v_add_f32_dpp v197, v197, v197 row_ror:8 row_mask:0xf bank_mask:0xf
	s_nop 1
	v_add_f32_dpp v197, v197, v197 row_ror:4 row_mask:0xf bank_mask:0xf
	s_nop 1
	v_add_f32_dpp v197, v197, v197 row_ror:2 row_mask:0xf bank_mask:0xf
	s_nop 1
	v_add_f32_dpp v197, v197, v197 row_ror:1 row_mask:0xf bank_mask:0xf
	v_max_f32_e32 v198, v192, v197
	v_sub_f32_e32 v199, v192, v198
	v_sub_f32_e32 v200, v197, v198
	v_exp_f32_e32 v199, v199
	v_exp_f32_e32 v200, v200
	v_mov_b32_e32 v192, v198
	v_fma_f32 v193, v193, v199, v200
	v_mul_f32_e32 v168, v168, v199
	v_mul_f32_e32 v169, v169, v199
	v_mul_f32_e32 v170, v170, v199
	v_mul_f32_e32 v171, v171, v199
	v_mul_f32_e32 v172, v172, v199
	v_mul_f32_e32 v173, v173, v199
	v_mul_f32_e32 v174, v174, v199
	v_mul_f32_e32 v175, v175, v199
	v_fmac_f32_e32 v168, v200, v104
	v_fmac_f32_e32 v169, v200, v105
	v_fmac_f32_e32 v170, v200, v106
	v_fmac_f32_e32 v171, v200, v107
	v_fmac_f32_e32 v172, v200, v108
	v_fmac_f32_e32 v173, v200, v109
	v_fmac_f32_e32 v174, v200, v110
	v_fmac_f32_e32 v175, v200, v111
	v_add_f32_e32 v194, v194, v196
	v_add_u32_e32 v195, s42, v195
	global_load_dwordx4 v[96:99], v195, s[20:21] nt
	global_load_dwordx4 v[100:103], v195, s[20:21] offset:256 nt
	global_load_dwordx4 v[104:107], v195, s[24:25] nt
	global_load_dwordx4 v[108:111], v195, s[24:25] offset:256 nt
	s_waitcnt vmcnt(28)
	v_fma_f32 v197, v160, v112, v194
	v_fmac_f32_e32 v197, v161, v113
	v_fmac_f32_e32 v197, v162, v114
	v_fmac_f32_e32 v197, v163, v115
	v_fmac_f32_e32 v197, v164, v116
	v_fmac_f32_e32 v197, v165, v117
	v_fmac_f32_e32 v197, v166, v118
	v_fmac_f32_e32 v197, v167, v119
	s_nop 1
	v_add_f32_dpp v197, v197, v197 row_ror:8 row_mask:0xf bank_mask:0xf
	s_nop 1
	v_add_f32_dpp v197, v197, v197 row_ror:4 row_mask:0xf bank_mask:0xf
	s_nop 1
	v_add_f32_dpp v197, v197, v197 row_ror:2 row_mask:0xf bank_mask:0xf
	s_nop 1
	v_add_f32_dpp v197, v197, v197 row_ror:1 row_mask:0xf bank_mask:0xf
	v_max_f32_e32 v198, v192, v197
	v_sub_f32_e32 v199, v192, v198
	v_sub_f32_e32 v200, v197, v198
	v_exp_f32_e32 v199, v199
	v_exp_f32_e32 v200, v200
	v_mov_b32_e32 v192, v198
	v_fma_f32 v193, v193, v199, v200
	v_mul_f32_e32 v168, v168, v199
	v_mul_f32_e32 v169, v169, v199
	v_mul_f32_e32 v170, v170, v199
	v_mul_f32_e32 v171, v171, v199
	v_mul_f32_e32 v172, v172, v199
	v_mul_f32_e32 v173, v173, v199
	v_mul_f32_e32 v174, v174, v199
	v_mul_f32_e32 v175, v175, v199
	v_fmac_f32_e32 v168, v200, v120
	v_fmac_f32_e32 v169, v200, v121
	v_fmac_f32_e32 v170, v200, v122
	v_fmac_f32_e32 v171, v200, v123
	v_fmac_f32_e32 v172, v200, v124
	v_fmac_f32_e32 v173, v200, v125
	v_fmac_f32_e32 v174, v200, v126
	v_fmac_f32_e32 v175, v200, v127
	v_add_f32_e32 v194, v194, v196
	v_add_u32_e32 v195, s42, v195
	global_load_dwordx4 v[112:115], v195, s[20:21] nt
	global_load_dwordx4 v[116:119], v195, s[20:21] offset:256 nt
	global_load_dwordx4 v[120:123], v195, s[24:25] nt
	global_load_dwordx4 v[124:127], v195, s[24:25] offset:256 nt
	s_add_u32 s33, s33, 1
	s_cmp_lt_u32 s33, 11
	s_cbranch_scc1 .Las_trip
; __device__ __forceinline__ float fexp2(float x) { return __builtin_amdgcn_exp2f(x); }
; __device__ __forceinline__ void attn_sample_item(const P& p, int wi, int lane) {
;     ...
;         for (int jj = 0; jj < 33; ++jj) {
;             const int j = 4 * jj + kg; const bool valid = j <= 128; const int jc = valid ? j : 128;
;             const int idx = 2048 + i - d * jc;
;             f32x4 k0, k1, v0, v1;
;             if (idx < 2048) { const size_t off = (((size_t)bs * 2048 + idx) * 8 + h) * 128 + 8 * li;
;                 k0 = __builtin_nontemporal_load((const f32x4*)(p.cache_k + off)); k1 = __builtin_nontemporal_load((const f32x4*)(p.cache_k + off + 4)); v0 = __builtin_nontemporal_load((const f32x4*)(p.cache_v + off)); v1 = __builtin_nontemporal_load((const f32x4*)(p.cache_v + off + 4)); }
;             else { const int nr = bs * 4 + (idx - 2048); const float rsn = rstd1[TP + nr]; const int c0 = 4096 + h * 128 + 8 * li;
;                 k0 = acc1_4(ACC1, nr, c0) * rsn; k1 = acc1_4(ACC1, nr, c0 + 4) * rsn; v0 = acc1_4(ACC1, nr, c0 + 1024) * rsn; v1 = acc1_4(ACC1, nr, c0 + 1028) * rsn; }
;             float dot = (q[0] * k0[0] + q[1] * k0[1]) + (q[2] * k0[2] + q[3] * k0[3]) + (q[4] * k1[0] + q[5] * k1[1]) + (q[6] * k1[2] + q[7] * k1[3]);
;             dot += __shfl_xor(dot, 1); dot += __shfl_xor(dot, 2); dot += __shfl_xor(dot, 4); dot += __shfl_xor(dot, 8);
;             const float s = valid ? dot - sl * (float)(d * j) : -INFINITY;
;             const float mn = fmaxf(m, s), sc = fexp2(m - mn), pe = fexp2(s - mn);
;             l = l * sc + pe;
;             acc[0] = acc[0] * sc + pe * v0[0]; acc[1] = acc[1] * sc + pe * v0[1]; acc[2] = acc[2] * sc + pe * v0[2]; acc[3] = acc[3] * sc + pe * v0[3];
;             acc[4] = acc[4] * sc + pe * v1[0]; acc[5] = acc[5] * sc + pe * v1[1]; acc[6] = acc[6] * sc + pe * v1[2]; acc[7] = acc[7] * sc + pe * v1[3];
;             m = mn;
;         }
	s_waitcnt vmcnt(28)
	v_fma_f32 v197, v160, v0, v194
	v_fmac_f32_e32 v197, v161, v1
	v_fmac_f32_e32 v197, v162, v2
	v_fmac_f32_e32 v197, v163, v3
	v_fmac_f32_e32 v197, v164, v4
	v_fmac_f32_e32 v197, v165, v5
	v_fmac_f32_e32 v197, v166, v6
	v_fmac_f32_e32 v197, v167, v7
	s_nop 1
	v_add_f32_dpp v197, v197, v197 row_ror:8 row_mask:0xf bank_mask:0xf
	s_nop 1
	v_add_f32_dpp v197, v197, v197 row_ror:4 row_mask:0xf bank_mask:0xf
	s_nop 1
	v_add_f32_dpp v197, v197, v197 row_ror:2 row_mask:0xf bank_mask:0xf
	s_nop 1
	v_add_f32_dpp v197, v197, v197 row_ror:1 row_mask:0xf bank_mask:0xf
	v_max_f32_e32 v198, v192, v197
	v_sub_f32_e32 v199, v192, v198
	v_sub_f32_e32 v200, v197, v198
	v_exp_f32_e32 v199, v199
	v_exp_f32_e32 v200, v200
	v_mov_b32_e32 v192, v198
	v_fma_f32 v193, v193, v199, v200
	v_mul_f32_e32 v168, v168, v199
	v_mul_f32_e32 v169, v169, v199
	v_mul_f32_e32 v170, v170, v199
	v_mul_f32_e32 v171, v171, v199
	v_mul_f32_e32 v172, v172, v199
	v_mul_f32_e32 v173, v173, v199
	v_mul_f32_e32 v174, v174, v199
	v_mul_f32_e32 v175, v175, v199
	v_fmac_f32_e32 v168, v200, v8
	v_fmac_f32_e32 v169, v200, v9
	v_fmac_f32_e32 v170, v200, v10
	v_fmac_f32_e32 v171, v200, v11
	v_fmac_f32_e32 v172, v200, v12
	v_fmac_f32_e32 v173, v200, v13
	v_fmac_f32_e32 v174, v200, v14
	v_fmac_f32_e32 v175, v200, v15
	v_add_f32_e32 v194, v194, v196
	s_waitcnt vmcnt(24)
	v_fma_f32 v197, v160, v16, v194
	v_fmac_f32_e32 v197, v161, v17
	v_fmac_f32_e32 v197, v162, v18
	v_fmac_f32_e32 v197, v163, v19
	v_fmac_f32_e32 v197, v164, v20
	v_fmac_f32_e32 v197, v165, v21
	v_fmac_f32_e32 v197, v166, v22
	v_fmac_f32_e32 v197, v167, v23
	s_nop 1
	v_add_f32_dpp v197, v197, v197 row_ror:8 row_mask:0xf bank_mask:0xf
	s_nop 1
	v_add_f32_dpp v197, v197, v197 row_ror:4 row_mask:0xf bank_mask:0xf
	s_nop 1
	v_add_f32_dpp v197, v197, v197 row_ror:2 row_mask:0xf bank_mask:0xf
	s_nop 1
	v_add_f32_dpp v197, v197, v197 row_ror:1 row_mask:0xf bank_mask:0xf
	v_max_f32_e32 v198, v192, v197
	v_sub_f32_e32 v199, v192, v198
	v_sub_f32_e32 v200, v197, v198
	v_exp_f32_e32 v199, v199
	v_exp_f32_e32 v200, v200
	v_mov_b32_e32 v192, v198
	v_fma_f32 v193, v193, v199, v200
	v_mul_f32_e32 v168, v168, v199
	v_mul_f32_e32 v169, v169, v199
	v_mul_f32_e32 v170, v170, v199
	v_mul_f32_e32 v171, v171, v199
	v_mul_f32_e32 v172, v172, v199
	v_mul_f32_e32 v173, v173, v199
	v_mul_f32_e32 v174, v174, v199
	v_mul_f32_e32 v175, v175, v199
	v_fmac_f32_e32 v168, v200, v24
	v_fmac_f32_e32 v169, v200, v25
	v_fmac_f32_e32 v170, v200, v26
	v_fmac_f32_e32 v171, v200, v27
	v_fmac_f32_e32 v172, v200, v28
	v_fmac_f32_e32 v173, v200, v29
	v_fmac_f32_e32 v174, v200, v30
	v_fmac_f32_e32 v175, v200, v31
	v_add_f32_e32 v194, v194, v196
	s_waitcnt vmcnt(20)
	v_fma_f32 v197, v160, v32, v194
	v_fmac_f32_e32 v197, v161, v33
	v_fmac_f32_e32 v197, v162, v34
	v_fmac_f32_e32 v197, v163, v35
	v_fmac_f32_e32 v197, v164, v36
	v_fmac_f32_e32 v197, v165, v37
	v_fmac_f32_e32 v197, v166, v38
	v_fmac_f32_e32 v197, v167, v39
	s_nop 1
	v_add_f32_dpp v197, v197, v197 row_ror:8 row_mask:0xf bank_mask:0xf
	s_nop 1
	v_add_f32_dpp v197, v197, v197 row_ror:4 row_mask:0xf bank_mask:0xf
	s_nop 1
	v_add_f32_dpp v197, v197, v197 row_ror:2 row_mask:0xf bank_mask:0xf
	s_nop 1
	v_add_f32_dpp v197, v197, v197 row_ror:1 row_mask:0xf bank_mask:0xf
	v_max_f32_e32 v198, v192, v197
	v_sub_f32_e32 v199, v192, v198
	v_sub_f32_e32 v200, v197, v198
	v_exp_f32_e32 v199, v199
	v_exp_f32_e32 v200, v200
	v_mov_b32_e32 v192, v198
	v_fma_f32 v193, v193, v199, v200
	v_mul_f32_e32 v168, v168, v199
	v_mul_f32_e32 v169, v169, v199
	v_mul_f32_e32 v170, v170, v199
	v_mul_f32_e32 v171, v171, v199
	v_mul_f32_e32 v172, v172, v199
	v_mul_f32_e32 v173, v173, v199
	v_mul_f32_e32 v174, v174, v199
	v_mul_f32_e32 v175, v175, v199
	v_fmac_f32_e32 v168, v200, v40
	v_fmac_f32_e32 v169, v200, v41
	v_fmac_f32_e32 v170, v200, v42
	v_fmac_f32_e32 v171, v200, v43
	v_fmac_f32_e32 v172, v200, v44
	v_fmac_f32_e32 v173, v200, v45
	v_fmac_f32_e32 v174, v200, v46
	v_fmac_f32_e32 v175, v200, v47
	v_add_f32_e32 v194, v194, v196
	s_waitcnt vmcnt(16)
	v_fma_f32 v197, v160, v48, v194
	v_fmac_f32_e32 v197, v161, v49
	v_fmac_f32_e32 v197, v162, v50
	v_fmac_f32_e32 v197, v163, v51
	v_fmac_f32_e32 v197, v164, v52
	v_fmac_f32_e32 v197, v165, v53
	v_fmac_f32_e32 v197, v166, v54
	v_fmac_f32_e32 v197, v167, v55
	s_nop 1
	v_add_f32_dpp v197, v197, v197 row_ror:8 row_mask:0xf bank_mask:0xf
	s_nop 1
	v_add_f32_dpp v197, v197, v197 row_ror:4 row_mask:0xf bank_mask:0xf
	s_nop 1
	v_add_f32_dpp v197, v197, v197 row_ror:2 row_mask:0xf bank_mask:0xf
	s_nop 1
	v_add_f32_dpp v197, v197, v197 row_ror:1 row_mask:0xf bank_mask:0xf
	v_max_f32_e32 v198, v192, v197
	v_sub_f32_e32 v199, v192, v198
	v_sub_f32_e32 v200, v197, v198
	v_exp_f32_e32 v199, v199
	v_exp_f32_e32 v200, v200
	v_mov_b32_e32 v192, v198
	v_fma_f32 v193, v193, v199, v200
	v_mul_f32_e32 v168, v168, v199
	v_mul_f32_e32 v169, v169, v199
	v_mul_f32_e32 v170, v170, v199
	v_mul_f32_e32 v171, v171, v199
	v_mul_f32_e32 v172, v172, v199
	v_mul_f32_e32 v173, v173, v199
	v_mul_f32_e32 v174, v174, v199
	v_mul_f32_e32 v175, v175, v199
	v_fmac_f32_e32 v168, v200, v56
	v_fmac_f32_e32 v169, v200, v57
	v_fmac_f32_e32 v170, v200, v58
	v_fmac_f32_e32 v171, v200, v59
	v_fmac_f32_e32 v172, v200, v60
	v_fmac_f32_e32 v173, v200, v61
	v_fmac_f32_e32 v174, v200, v62
	v_fmac_f32_e32 v175, v200, v63
	v_add_f32_e32 v194, v194, v196
	s_waitcnt vmcnt(12)
; __device__ __forceinline__ float fexp2(float x) { return __builtin_amdgcn_exp2f(x); }
; __device__ __forceinline__ void attn_sample_item(const P& p, int wi, int lane) {
;     ...
;         for (int jj = 0; jj < 33; ++jj) {
;             const int j = 4 * jj + kg; const bool valid = j <= 128; const int jc = valid ? j : 128;
;             const int idx = 2048 + i - d * jc;
;             f32x4 k0, k1, v0, v1;
;             if (idx < 2048) { const size_t off = (((size_t)bs * 2048 + idx) * 8 + h) * 128 + 8 * li;
;                 k0 = __builtin_nontemporal_load((const f32x4*)(p.cache_k + off)); k1 = __builtin_nontemporal_load((const f32x4*)(p.cache_k + off + 4)); v0 = __builtin_nontemporal_load((const f32x4*)(p.cache_v + off)); v1 = __builtin_nontemporal_load((const f32x4*)(p.cache_v + off + 4)); }
;             else { const int nr = bs * 4 + (idx - 2048); const float rsn = rstd1[TP + nr]; const int c0 = 4096 + h * 128 + 8 * li;
;                 k0 = acc1_4(ACC1, nr, c0) * rsn; k1 = acc1_4(ACC1, nr, c0 + 4) * rsn; v0 = acc1_4(ACC1, nr, c0 + 1024) * rsn; v1 = acc1_4(ACC1, nr, c0 + 1028) * rsn; }
;             float dot = (q[0] * k0[0] + q[1] * k0[1]) + (q[2] * k0[2] + q[3] * k0[3]) + (q[4] * k1[0] + q[5] * k1[1]) + (q[6] * k1[2] + q[7] * k1[3]);
;             dot += __shfl_xor(dot, 1); dot += __shfl_xor(dot, 2); dot += __shfl_xor(dot, 4); dot += __shfl_xor(dot, 8);
;             const float s = valid ? dot - sl * (float)(d * j) : -INFINITY;
;             const float mn = fmaxf(m, s), sc = fexp2(m - mn), pe = fexp2(s - mn);
;             l = l * sc + pe;
;             acc[0] = acc[0] * sc + pe * v0[0]; acc[1] = acc[1] * sc + pe * v0[1]; acc[2] = acc[2] * sc + pe * v0[2]; acc[3] = acc[3] * sc + pe * v0[3];
;             acc[4] = acc[4] * sc + pe * v1[0]; acc[5] = acc[5] * sc + pe * v1[1]; acc[6] = acc[6] * sc + pe * v1[2]; acc[7] = acc[7] * sc + pe * v1[3];
;             m = mn;
;         }
	v_fma_f32 v197, v160, v64, v194
	v_fmac_f32_e32 v197, v161, v65
	v_fmac_f32_e32 v197, v162, v66
	v_fmac_f32_e32 v197, v163, v67
	v_fmac_f32_e32 v197, v164, v68
	v_fmac_f32_e32 v197, v165, v69
	v_fmac_f32_e32 v197, v166, v70
	v_fmac_f32_e32 v197, v167, v71
	s_nop 1
	v_add_f32_dpp v197, v197, v197 row_ror:8 row_mask:0xf bank_mask:0xf
	s_nop 1
	v_add_f32_dpp v197, v197, v197 row_ror:4 row_mask:0xf bank_mask:0xf
	s_nop 1
	v_add_f32_dpp v197, v197, v197 row_ror:2 row_mask:0xf bank_mask:0xf
	s_nop 1
	v_add_f32_dpp v197, v197, v197 row_ror:1 row_mask:0xf bank_mask:0xf
	v_max_f32_e32 v198, v192, v197
	v_sub_f32_e32 v199, v192, v198
	v_sub_f32_e32 v200, v197, v198
	v_exp_f32_e32 v199, v199
	v_exp_f32_e32 v200, v200
	v_mov_b32_e32 v192, v198
	v_fma_f32 v193, v193, v199, v200
	v_mul_f32_e32 v168, v168, v199
	v_mul_f32_e32 v169, v169, v199
	v_mul_f32_e32 v170, v170, v199
	v_mul_f32_e32 v171, v171, v199
	v_mul_f32_e32 v172, v172, v199
	v_mul_f32_e32 v173, v173, v199
	v_mul_f32_e32 v174, v174, v199
	v_mul_f32_e32 v175, v175, v199
	v_fmac_f32_e32 v168, v200, v72
	v_fmac_f32_e32 v169, v200, v73
	v_fmac_f32_e32 v170, v200, v74
	v_fmac_f32_e32 v171, v200, v75
	v_fmac_f32_e32 v172, v200, v76
	v_fmac_f32_e32 v173, v200, v77
	v_fmac_f32_e32 v174, v200, v78
	v_fmac_f32_e32 v175, v200, v79
	v_add_f32_e32 v194, v194, v196
	s_waitcnt vmcnt(8)
	v_fma_f32 v197, v160, v80, v194
	v_fmac_f32_e32 v197, v161, v81
	v_fmac_f32_e32 v197, v162, v82
	v_fmac_f32_e32 v197, v163, v83
	v_fmac_f32_e32 v197, v164, v84
	v_fmac_f32_e32 v197, v165, v85
	v_fmac_f32_e32 v197, v166, v86
	v_fmac_f32_e32 v197, v167, v87
	s_nop 1
	v_add_f32_dpp v197, v197, v197 row_ror:8 row_mask:0xf bank_mask:0xf
	s_nop 1
	v_add_f32_dpp v197, v197, v197 row_ror:4 row_mask:0xf bank_mask:0xf
	s_nop 1
	v_add_f32_dpp v197, v197, v197 row_ror:2 row_mask:0xf bank_mask:0xf
	s_nop 1
	v_add_f32_dpp v197, v197, v197 row_ror:1 row_mask:0xf bank_mask:0xf
	v_max_f32_e32 v198, v192, v197
	v_sub_f32_e32 v199, v192, v198
	v_sub_f32_e32 v200, v197, v198
	v_exp_f32_e32 v199, v199
	v_exp_f32_e32 v200, v200
	v_mov_b32_e32 v192, v198
	v_fma_f32 v193, v193, v199, v200
	v_mul_f32_e32 v168, v168, v199
	v_mul_f32_e32 v169, v169, v199
	v_mul_f32_e32 v170, v170, v199
	v_mul_f32_e32 v171, v171, v199
	v_mul_f32_e32 v172, v172, v199
	v_mul_f32_e32 v173, v173, v199
	v_mul_f32_e32 v174, v174, v199
	v_mul_f32_e32 v175, v175, v199
	v_fmac_f32_e32 v168, v200, v88
	v_fmac_f32_e32 v169, v200, v89
	v_fmac_f32_e32 v170, v200, v90
	v_fmac_f32_e32 v171, v200, v91
	v_fmac_f32_e32 v172, v200, v92
	v_fmac_f32_e32 v173, v200, v93
	v_fmac_f32_e32 v174, v200, v94
	v_fmac_f32_e32 v175, v200, v95
	v_add_f32_e32 v194, v194, v196
	s_waitcnt vmcnt(4)
	v_fma_f32 v197, v160, v96, v194
	v_fmac_f32_e32 v197, v161, v97
	v_fmac_f32_e32 v197, v162, v98
	v_fmac_f32_e32 v197, v163, v99
	v_fmac_f32_e32 v197, v164, v100
	v_fmac_f32_e32 v197, v165, v101
	v_fmac_f32_e32 v197, v166, v102
	v_fmac_f32_e32 v197, v167, v103
	s_nop 1
	v_add_f32_dpp v197, v197, v197 row_ror:8 row_mask:0xf bank_mask:0xf
	s_nop 1
	v_add_f32_dpp v197, v197, v197 row_ror:4 row_mask:0xf bank_mask:0xf
	s_nop 1
	v_add_f32_dpp v197, v197, v197 row_ror:2 row_mask:0xf bank_mask:0xf
	s_nop 1
	v_add_f32_dpp v197, v197, v197 row_ror:1 row_mask:0xf bank_mask:0xf
	v_max_f32_e32 v198, v192, v197
	v_sub_f32_e32 v199, v192, v198
	v_sub_f32_e32 v200, v197, v198
	v_exp_f32_e32 v199, v199
	v_exp_f32_e32 v200, v200
	v_mov_b32_e32 v192, v198
	v_fma_f32 v193, v193, v199, v200
	v_mul_f32_e32 v168, v168, v199
	v_mul_f32_e32 v169, v169, v199
	v_mul_f32_e32 v170, v170, v199
	v_mul_f32_e32 v171, v171, v199
	v_mul_f32_e32 v172, v172, v199
	v_mul_f32_e32 v173, v173, v199
	v_mul_f32_e32 v174, v174, v199
	v_mul_f32_e32 v175, v175, v199
	v_fmac_f32_e32 v168, v200, v104
	v_fmac_f32_e32 v169, v200, v105
	v_fmac_f32_e32 v170, v200, v106
	v_fmac_f32_e32 v171, v200, v107
	v_fmac_f32_e32 v172, v200, v108
	v_fmac_f32_e32 v173, v200, v109
	v_fmac_f32_e32 v174, v200, v110
	v_fmac_f32_e32 v175, v200, v111
	v_add_f32_e32 v194, v194, v196
	s_waitcnt vmcnt(0)
; __device__ __forceinline__ float fexp2(float x) { return __builtin_amdgcn_exp2f(x); }
; __device__ __forceinline__ void attn_sample_item(const P& p, int wi, int lane) {
;     ...
;             float dot = (q[0] * k0[0] + q[1] * k0[1]) + (q[2] * k0[2] + q[3] * k0[3]) + (q[4] * k1[0] + q[5] * k1[1]) + (q[6] * k1[2] + q[7] * k1[3]);
;             dot += __shfl_xor(dot, 1); dot += __shfl_xor(dot, 2); dot += __shfl_xor(dot, 4); dot += __shfl_xor(dot, 8);
;             const float s = valid ? dot - sl * (float)(d * j) : -INFINITY;
;             const float mn = fmaxf(m, s), sc = fexp2(m - mn), pe = fexp2(s - mn);
;             l = l * sc + pe;
;             acc[0] = acc[0] * sc + pe * v0[0]; acc[1] = acc[1] * sc + pe * v0[1]; acc[2] = acc[2] * sc + pe * v0[2]; acc[3] = acc[3] * sc + pe * v0[3];
;             acc[4] = acc[4] * sc + pe * v1[0]; acc[5] = acc[5] * sc + pe * v1[1]; acc[6] = acc[6] * sc + pe * v1[2]; acc[7] = acc[7] * sc + pe * v1[3];
;             m = mn;
;         }
;     }
;     float mt = fmaxf(m, __shfl_xor(m, 16)); mt = fmaxf(mt, __shfl_xor(mt, 32));
;     const float f = fexp2(m - mt);
;     l *= f; l += __shfl_xor(l, 16); l += __shfl_xor(l, 32);
;     const float inv = 1.f / l;
;     float* o = (float*)(ws + O_ATTS) + (size_t)srow * 1024 + h * 128 + 8 * li;
; #pragma unroll
;     for (int e = 0; e < 8; ++e) { float a = acc[e] * f; a += __shfl_xor(a, 16); a += __shfl_xor(a, 32); acc[e] = a * inv; }
;     if (kg == 0) { *(f32x4*)o = (f32x4){acc[0], acc[1], acc[2], acc[3]}; *(f32x4*)(o + 4) = (f32x4){acc[4], acc[5], acc[6], acc[7]}; }
	v_fma_f32 v197, v160, v112, v194
	v_fmac_f32_e32 v197, v161, v113
	v_fmac_f32_e32 v197, v162, v114
	v_fmac_f32_e32 v197, v163, v115
	v_fmac_f32_e32 v197, v164, v116
	v_fmac_f32_e32 v197, v165, v117
	v_fmac_f32_e32 v197, v166, v118
	v_fmac_f32_e32 v197, v167, v119
	s_nop 1
	v_add_f32_dpp v197, v197, v197 row_ror:8 row_mask:0xf bank_mask:0xf
	s_nop 1
	v_add_f32_dpp v197, v197, v197 row_ror:4 row_mask:0xf bank_mask:0xf
	s_nop 1
	v_add_f32_dpp v197, v197, v197 row_ror:2 row_mask:0xf bank_mask:0xf
	s_nop 1
	v_add_f32_dpp v197, v197, v197 row_ror:1 row_mask:0xf bank_mask:0xf
	v_max_f32_e32 v198, v192, v197
	v_sub_f32_e32 v199, v192, v198
	v_sub_f32_e32 v200, v197, v198
	v_exp_f32_e32 v199, v199
	v_exp_f32_e32 v200, v200
	v_mov_b32_e32 v192, v198
	v_fma_f32 v193, v193, v199, v200
	v_mul_f32_e32 v168, v168, v199
	v_mul_f32_e32 v169, v169, v199
	v_mul_f32_e32 v170, v170, v199
	v_mul_f32_e32 v171, v171, v199
	v_mul_f32_e32 v172, v172, v199
	v_mul_f32_e32 v173, v173, v199
	v_mul_f32_e32 v174, v174, v199
	v_mul_f32_e32 v175, v175, v199
	v_fmac_f32_e32 v168, v200, v120
	v_fmac_f32_e32 v169, v200, v121
	v_fmac_f32_e32 v170, v200, v122
	v_fmac_f32_e32 v171, v200, v123
	v_fmac_f32_e32 v172, v200, v124
	v_fmac_f32_e32 v173, v200, v125
	v_fmac_f32_e32 v174, v200, v126
	v_fmac_f32_e32 v175, v200, v127
	v_and_b32_e32 v182, 63, v230
	v_xor_b32_e32 v183, 16, v182
	v_lshlrev_b32_e32 v183, 2, v183
	v_xor_b32_e32 v182, 32, v182
	v_lshlrev_b32_e32 v182, 2, v182
	ds_bpermute_b32 v197, v183, v192
	s_waitcnt lgkmcnt(0)
	v_max_f32_e32 v198, v192, v197
	ds_bpermute_b32 v197, v182, v198
	s_waitcnt lgkmcnt(0)
	v_max_f32_e32 v198, v198, v197
	v_sub_f32_e32 v199, v192, v198
	v_exp_f32_e32 v199, v199
	s_nop 0
	v_mul_f32_e32 v193, v193, v199
	v_mul_f32_e32 v168, v168, v199
	v_mul_f32_e32 v169, v169, v199
	v_mul_f32_e32 v170, v170, v199
	v_mul_f32_e32 v171, v171, v199
	v_mul_f32_e32 v172, v172, v199
	v_mul_f32_e32 v173, v173, v199
	v_mul_f32_e32 v174, v174, v199
	v_mul_f32_e32 v175, v175, v199
	ds_bpermute_b32 v0, v183, v193
	ds_bpermute_b32 v1, v183, v168
	ds_bpermute_b32 v2, v183, v169
	ds_bpermute_b32 v3, v183, v170
	ds_bpermute_b32 v4, v183, v171
	ds_bpermute_b32 v5, v183, v172
	ds_bpermute_b32 v6, v183, v173
	ds_bpermute_b32 v7, v183, v174
	ds_bpermute_b32 v8, v183, v175
	s_waitcnt lgkmcnt(0)
	v_add_f32_e32 v193, v193, v0
	v_add_f32_e32 v168, v168, v1
	v_add_f32_e32 v169, v169, v2
	v_add_f32_e32 v170, v170, v3
	v_add_f32_e32 v171, v171, v4
	v_add_f32_e32 v172, v172, v5
	v_add_f32_e32 v173, v173, v6
	v_add_f32_e32 v174, v174, v7
	v_add_f32_e32 v175, v175, v8
	ds_bpermute_b32 v0, v182, v193
	ds_bpermute_b32 v1, v182, v168
	ds_bpermute_b32 v2, v182, v169
	ds_bpermute_b32 v3, v182, v170
	ds_bpermute_b32 v4, v182, v171
	ds_bpermute_b32 v5, v182, v172
	ds_bpermute_b32 v6, v182, v173
	ds_bpermute_b32 v7, v182, v174
	ds_bpermute_b32 v8, v182, v175
	s_waitcnt lgkmcnt(0)
	v_add_f32_e32 v193, v193, v0
	v_add_f32_e32 v168, v168, v1
	v_add_f32_e32 v169, v169, v2
	v_add_f32_e32 v170, v170, v3
	v_add_f32_e32 v171, v171, v4
	v_add_f32_e32 v172, v172, v5
	v_add_f32_e32 v173, v173, v6
	v_add_f32_e32 v174, v174, v7
	v_add_f32_e32 v175, v175, v8
	v_rcp_f32_e32 v197, v193
	s_nop 0
	v_fma_f32 v198, -v193, v197, 1.0
	v_fma_f32 v197, v198, v197, v197
	v_mul_f32_e32 v168, v168, v197
	v_mul_f32_e32 v169, v169, v197
	v_mul_f32_e32 v170, v170, v197
	v_mul_f32_e32 v171, v171, v197
	v_mul_f32_e32 v172, v172, v197
	v_mul_f32_e32 v173, v173, v197
	v_mul_f32_e32 v174, v174, v197
	v_mul_f32_e32 v175, v175, v197
	v_and_b32_e32 v182, 15, v230
	v_lshlrev_b32_e32 v182, 4, v182
	s_lshl_b32 s43, s17, 12
	s_add_u32 s43, s43, s23
	v_add_u32_e32 v182, s43, v182
	s_mov_b64 exec, 0xffff
	global_store_dwordx4 v182, v[168:171], s[30:31]
	global_store_dwordx4 v182, v[172:175], s[30:31] offset:256
	s_mov_b64 exec, -1
	s_add_i32 s3, s3, s77
	s_cmpk_gt_i32 s3, 0x3ff
	s_cbranch_scc0 .Las_item
